# M1 RG-LRU pre-pass: causal conv loads issued together with wave-uniform scalar control flow (one wait per unit instead of ~20 serialized round trips); same f32 math and order
# speedup vs baseline: 1.0514x; 1.0105x over previous
; __device__ __forceinline__ float bf2f(bf16_t h) { return __uint_as_float((unsigned)h << 16); }
; __device__ __forceinline__ bf16_t f2bf(float f) { return (bf16_t)(cvt_pk_bf16(f, 0.f) & 0xffffu); }
; __device__ __forceinline__ void phase_m1(PP P, int l, LAS unsigned char* lds, const Ids I) {
;     ...
;             const float* cw = P->in[I_CONVW] + (size_t)l * 4 * 512; const float cwv[4] = {cw[chg], cw[512 + chg], cw[1024 + chg], cw[1536 + chg]}; const float cb = P->in[I_CONVB][l * 512 + chg];
; #pragma unroll
;             for (int i = 0; i < 8; ++i) { const int r = r0 + tg * 8 + i, t = t_in_seq(r); float a = cb;
; #pragma unroll
;                 for (int j = 0; j < 4; ++j) { const int ts = t - 3 + j; float xv;
;                     if (ts >= 0) xv = bf2f(PR[(size_t)(r - 3 + j) * INW + chg]);
;                     else xv = (r < MTP) ? 0.f : P->in[I_SCONV][(((size_t)l * 128 + ((r - MTP) >> 2)) * 3 + (ts + 3)) * 512 + chg];
;                     a += xv * cwv[j]; }
;                 XC[d * 68 + tg * 8 + i] = a; XB[(tg * 8 + i) * 72 + d] = f2bf(a); }
.LBB0_94:
	s_load_dwordx4 s[28:31], s[88:89], 0x88
	s_load_dwordx2 s[20:21], s[88:89], 0x20
	s_and_b32 s25, s0, 0xffffffc0
	v_or_b32_e32 v40, s3, v66
	v_lshlrev_b32_e32 v144, 2, v40
	v_lshlrev_b32_e32 v41, 1, v40
	s_lshr_b32 s4, s62, 3
	s_add_i32 s26, s25, s4
	v_or_b32_e32 v32, s27, v40
	v_lshlrev_b32_e32 v32, 2, v32
	s_waitcnt lgkmcnt(0)
	s_add_u32 s4, s28, s24
	s_addc_u32 s5, s29, 0
	global_load_dword v37, v144, s[4:5]
	global_load_dword v36, v144, s[4:5] offset:2048
	s_add_u32 s4, s4, 0x1000
	s_addc_u32 s5, s5, 0
	global_load_dword v38, v144, s[4:5]
	global_load_dword v34, v144, s[4:5] offset:2048
	global_load_dword v35, v32, s[30:31]
	s_cmp_ge_i32 s26, s91
	s_cbranch_scc1 .Lcv_sample
	s_add_i32 s18, s26, -3
	s_mul_hi_i32 s19, s18, s73
	s_mul_i32 s18, s18, s73
	s_add_u32 s18, s60, s18
	s_addc_u32 s19, s61, s19
	global_load_ushort v116, v41, s[18:19]
	s_add_u32 s18, s18, 0x1600
	s_addc_u32 s19, s19, 0
	global_load_ushort v117, v41, s[18:19]
	s_add_u32 s18, s18, 0x1600
	s_addc_u32 s19, s19, 0
	global_load_ushort v118, v41, s[18:19]
	s_add_u32 s18, s18, 0x1600
	s_addc_u32 s19, s19, 0
	global_load_ushort v119, v41, s[18:19]
	s_add_u32 s18, s18, 0x1600
	s_addc_u32 s19, s19, 0
	global_load_ushort v120, v41, s[18:19]
	s_add_u32 s18, s18, 0x1600
	s_addc_u32 s19, s19, 0
	global_load_ushort v121, v41, s[18:19]
	s_add_u32 s18, s18, 0x1600
	s_addc_u32 s19, s19, 0
	global_load_ushort v122, v41, s[18:19]
	s_add_u32 s18, s18, 0x1600
	s_addc_u32 s19, s19, 0
	global_load_ushort v126, v41, s[18:19]
	s_add_u32 s18, s18, 0x1600
	s_addc_u32 s19, s19, 0
	global_load_ushort v127, v41, s[18:19]
	s_add_u32 s18, s18, 0x1600
	s_addc_u32 s19, s19, 0
	global_load_ushort v128, v41, s[18:19]
	s_add_u32 s18, s18, 0x1600
	s_addc_u32 s19, s19, 0
	global_load_ushort v129, v41, s[18:19]
	s_and_b32 s4, s26, 0x7ff
	s_waitcnt vmcnt(0)
	v_lshlrev_b32_e32 v116, 16, v116
	v_lshlrev_b32_e32 v117, 16, v117
	v_lshlrev_b32_e32 v118, 16, v118
	v_lshlrev_b32_e32 v119, 16, v119
	v_lshlrev_b32_e32 v120, 16, v120
	v_lshlrev_b32_e32 v121, 16, v121
	v_lshlrev_b32_e32 v122, 16, v122
	v_lshlrev_b32_e32 v126, 16, v126
	v_lshlrev_b32_e32 v127, 16, v127
	v_lshlrev_b32_e32 v128, 16, v128
	v_lshlrev_b32_e32 v129, 16, v129
	s_cmp_lg_u32 s4, 0
	s_cbranch_scc1 .Lcv_nozero
	v_mov_b32_e32 v116, 0
	v_mov_b32_e32 v117, 0
	v_mov_b32_e32 v118, 0
.Lcv_nozero:
	v_mov_b32_e32 v123, v120
	v_mov_b32_e32 v124, v121
	v_mov_b32_e32 v125, v122
	s_branch .Lcv_fma
.Lcv_sample:
	s_mul_hi_u32 s19, s26, s73
	s_mul_i32 s18, s26, s73
	s_add_u32 s18, s60, s18
	s_addc_u32 s19, s61, s19
	global_load_ushort v119, v41, s[18:19]
	s_add_u32 s18, s18, 0x1600
	s_addc_u32 s19, s19, 0
	global_load_ushort v120, v41, s[18:19]
	s_add_u32 s18, s18, 0x1600
	s_addc_u32 s19, s19, 0
	global_load_ushort v121, v41, s[18:19]
	s_add_u32 s18, s18, 0x1600
	s_addc_u32 s19, s19, 0
	global_load_ushort v122, v41, s[18:19]
	s_add_u32 s18, s18, 0x1600
	s_addc_u32 s19, s19, 0
	global_load_ushort v126, v41, s[18:19]
	s_add_u32 s18, s18, 0x1600
	s_addc_u32 s19, s19, 0
	global_load_ushort v127, v41, s[18:19]
	s_add_u32 s18, s18, 0x1600
	s_addc_u32 s19, s19, 0
	global_load_ushort v128, v41, s[18:19]
	s_add_u32 s18, s18, 0x1600
	s_addc_u32 s19, s19, 0
	global_load_ushort v129, v41, s[18:19]
	s_sub_i32 s4, s26, s91
	s_lshr_b32 s4, s4, 2
	s_add_i32 s4, s4, s34
	s_mul_i32 s4, s4, 0x1800
	s_add_u32 s18, s20, s4
	s_addc_u32 s19, s21, 0
	global_load_dword v116, v144, s[18:19]
	global_load_dword v117, v144, s[18:19] offset:2048
	s_add_u32 s18, s18, 0x1000
	s_addc_u32 s19, s19, 0
	global_load_dword v118, v144, s[18:19]
	global_load_dword v123, v144, s[18:19] offset:2048
	s_add_u32 s18, s18, 0x1000
	s_addc_u32 s19, s19, 0
	global_load_dword v124, v144, s[18:19]
	global_load_dword v125, v144, s[18:19] offset:2048
	s_waitcnt vmcnt(0)
	v_lshlrev_b32_e32 v119, 16, v119
	v_lshlrev_b32_e32 v120, 16, v120
	v_lshlrev_b32_e32 v121, 16, v121
	v_lshlrev_b32_e32 v122, 16, v122
	v_lshlrev_b32_e32 v126, 16, v126
	v_lshlrev_b32_e32 v127, 16, v127
	v_lshlrev_b32_e32 v128, 16, v128
	v_lshlrev_b32_e32 v129, 16, v129
.Lcv_fma:
	v_fma_f32 v130, v37, v116, v35
	v_fmac_f32_e32 v130, v36, v117
	v_fmac_f32_e32 v130, v38, v118
	v_fmac_f32_e32 v130, v34, v119
	v_fma_f32 v131, v37, v117, v35
	v_fmac_f32_e32 v131, v36, v118
	v_fmac_f32_e32 v131, v38, v119
	v_fmac_f32_e32 v131, v34, v120
	v_fma_f32 v132, v37, v118, v35
	v_fmac_f32_e32 v132, v36, v119
	v_fmac_f32_e32 v132, v38, v120
	v_fmac_f32_e32 v132, v34, v121
	v_fma_f32 v133, v37, v119, v35
	v_fmac_f32_e32 v133, v36, v120
	v_fmac_f32_e32 v133, v38, v121
	v_fmac_f32_e32 v133, v34, v122
	v_fma_f32 v134, v37, v123, v35
	v_fmac_f32_e32 v134, v36, v124
	v_fmac_f32_e32 v134, v38, v125
	v_fmac_f32_e32 v134, v34, v126
	v_fma_f32 v135, v37, v124, v35
	v_fmac_f32_e32 v135, v36, v125
	v_fmac_f32_e32 v135, v38, v126
	v_fmac_f32_e32 v135, v34, v127
	v_fma_f32 v136, v37, v125, v35
	v_fmac_f32_e32 v136, v36, v126
	v_fmac_f32_e32 v136, v38, v127
	v_fmac_f32_e32 v136, v34, v128
	v_fma_f32 v137, v37, v126, v35
	v_fmac_f32_e32 v137, v36, v127
	v_fmac_f32_e32 v137, v38, v128
	v_fmac_f32_e32 v137, v34, v129
	ds_write_b128 v68, v[130:133]
	ds_write_b128 v68, v[134:137] offset:16
	v_cvt_pk_bf16_f32 v138, v130, v145
	ds_write_b16 v81, v138 offset:17408
	v_cvt_pk_bf16_f32 v139, v131, v145
	ds_write_b16 v81, v139 offset:17552
	v_cvt_pk_bf16_f32 v140, v132, v145
	ds_write_b16 v81, v140 offset:17696
	v_cvt_pk_bf16_f32 v141, v133, v145
	ds_write_b16 v81, v141 offset:17840
	v_cvt_pk_bf16_f32 v138, v134, v145
	ds_write_b16 v81, v138 offset:17984
	v_cvt_pk_bf16_f32 v139, v135, v145
	ds_write_b16 v81, v139 offset:18128
	v_cvt_pk_bf16_f32 v140, v136, v145
	ds_write_b16 v81, v140 offset:18272
	v_cvt_pk_bf16_f32 v141, v137, v145
	ds_write_b16 v81, v141 offset:18416
	v_cndmask_b32_e64 v55, 0, 1, s[8:9]
	s_mov_b64 s[18:19], -1
	v_cmp_ne_u32_e64 s[4:5], 1, v55
	s_andn2_b64 vcc, exec, s[8:9]
	v_add_u32_e32 v55, v85, v70
	s_waitcnt lgkmcnt(0)
	s_barrier
	ds_read_b128 v[32:35], v79 offset:17408
	ds_read_b128 v[86:89], v79 offset:17472
	s_waitcnt lgkmcnt(1)
	v_mfma_f32_16x16x32_bf16 v[36:39], v[32:35], v[0:3], 0
	s_waitcnt lgkmcnt(0)
	v_mfma_f32_16x16x32_bf16 v[44:47], v[86:89], v[4:7], v[36:39]
	v_mfma_f32_16x16x32_bf16 v[40:43], v[32:35], v[8:11], 0
	v_mfma_f32_16x16x32_bf16 v[90:93], v[32:35], v[16:19], 0
	s_nop 5
	v_add_f32_e32 v44, v49, v44
	v_mul_f32_e32 v44, 0xbfb8aa3b, v44
	v_exp_f32_e32 v44, v44
	v_mfma_f32_16x16x32_bf16 v[32:35], v[32:35], v[24:27], 0
	v_add_f32_e32 v44, 1.0, v44
	v_mfma_f32_16x16x32_bf16 v[40:43], v[86:89], v[12:15], v[40:43]
	v_rcp_f32_e32 v44, v44
	v_mfma_f32_16x16x32_bf16 v[36:39], v[86:89], v[20:23], v[90:93]
	v_mfma_f32_16x16x32_bf16 v[32:35], v[86:89], v[28:31], v[32:35]
	s_cbranch_vccnz .LBB0_142
	v_mul_f32_e32 v57, 0xc1000000, v44
	v_mul_f32_e32 v57, v60, v57
	s_mov_b64 s[18:19], 0
	v_cvt_pk_bf16_f32 v57, v57, v145
	ds_write_b16 v55, v57 offset:26624

; #define LAS __attribute__((address_space(3)))
; __device__ __forceinline__ bf16_t f2bf(float f) { return (bf16_t)(cvt_pk_bf16(f, 0.f) & 0xffffu); }
; __device__ __forceinline__ float sigmoidf(float x) { return rcpf(1.0f + __expf(-x)); }
; __device__ __forceinline__ void phase_m1(PP P, int l, LAS unsigned char* lds, const Ids I) {
;     ...
;                 for (int j = 0; j < 4; ++j) { const int tok = mt * 16 + quad * 4 + j; const float g = sigmoidf(acc[nt][j] + bias4[nt]);
;                     if (half) OB[tok * 64 + dd] = f2bf(-8.0f * g * sp4[nt]);
;                     else OB[4096 + tok * 64 + dd] = f2bf(g * XC[dd * 68 + tok]); } }
;             __syncthreads();
; #pragma unroll
;             for (int i = 0; i < 2; ++i) { const int idx = tid + 512 * i, a = idx >> 9, rem = idx & 511, tok = rem >> 3, c8 = (rem & 7) * 8;
;                 *(u32x4*)(arr + (a == 0 ? A_LA : A_GX) * AS + (size_t)(r0 + tok) * 512 + n * 64 + c8) = *(const LAS u32x4*)(OB + a * 4096 + tok * 64 + c8); }
;             __syncthreads();
.LBB0_202:
	s_andn2_b64 vcc, exec, s[4:5]
	s_cbranch_vccnz .LBB0_91
	ds_read_b32 v33, v78 offset:12
	s_waitcnt lgkmcnt(0)
	v_mul_f32_e32 v32, v32, v33
	v_cvt_pk_bf16_f32 v32, v32, v145
	ds_write_b16 v40, v32 offset:34912
	s_branch .LBB0_91
.LBB0_206:
	s_or_b64 exec, exec, s[14:15]
	s_xor_b64 s[12:13], s[16:17], -1
	s_and_saveexec_b64 s[14:15], s[12:13]
	s_xor_b64 s[14:15], exec, s[14:15]
	s_cbranch_execz .LBB0_209
	s_mov_b64 s[12:13], exec
	v_mbcnt_lo_u32_b32 v0, s12, 0
	v_mbcnt_hi_u32_b32 v0, s13, v0
	v_cmp_eq_u32_e32 vcc, 0, v0
	s_and_b64 s[14:15], exec, vcc
	s_mov_b64 exec, s[14:15]
	s_cbranch_execz .LBB0_209
	s_bcnt1_i32_b64 s12, s[12:13]
	v_mov_b32_e32 v0, s12
	global_atomic_add v145, v0, s[4:5]
